# v17 + x-pointer loads hoisted out of the prologue norm loop + attention unit start issues K/V tile DMAs before the Q loads (one wait) + next-unit queue claim issued while the current unit finishes
# baseline (speedup 1.0000x reference)
; #define GAS __attribute__((address_space(1)))
; __device__ __forceinline__ void p0_prologue(KArgs A, unsigned char* ws, LAS unsigned char* lds, int vcu, int G, int wave, int lane) {
;     ...
;     bf16* XB = (bf16*)(ws + WS_XB); float* RSTD1 = (float*)(ws + WS_RSTD1); float* RSS = (float*)(ws + WS_SSQP);
; #pragma nounroll
;     for (int m = gw; m < MALL; m += 4 * NGW) {
;         f32x4 v[4][4]; int mr[4]; bool has[4];
; #pragma unroll
;         for (int r = 0; r < 4; ++r) { const int mm = m + r * NGW; has[r] = mm < MALL; mr[r] = has[r] ? mm : m;
;             const float* xr = mr[r] < MP ? A->in.xp + (size_t)mr[r] * DM : A->in.xs + (size_t)(mr[r] - MP) * DM; const GAS f32x4* p = (const GAS f32x4*)xr + lane;
.LBB0_83:
	s_cmpk_gt_i32 s14, 0x41ff
	v_mov_b32_e32 v67, 0
	v_cmp_eq_u32_e64 s[6:7], 0, v230
	s_cbranch_scc1 .LBB0_100
	v_mbcnt_hi_u32_b32 v2, -1, v163
	v_and_b32_e32 v1, 64, v2
	v_add_u32_e32 v3, 64, v1
	v_xor_b32_e32 v1, 1, v2
	v_cmp_lt_i32_e32 vcc, v1, v3
	v_xor_b32_e32 v4, 2, v2
	s_load_dwordx2 s[98:99], s[12:13], 0x0
	s_load_dwordx2 s[100:101], s[12:13], 0x8
	s_waitcnt lgkmcnt(0)
	s_add_u32 s1, s16, 0x1e00000
	v_cndmask_b32_e32 v1, v2, v1, vcc
	v_cmp_lt_i32_e32 vcc, v4, v3
	s_addc_u32 s2, s17, 0
	v_lshlrev_b32_e32 v66, 3, v230
	v_cndmask_b32_e32 v4, v2, v4, vcc
	v_lshlrev_b32_e32 v70, 2, v4
	v_xor_b32_e32 v4, 4, v2
	v_cmp_lt_i32_e32 vcc, v4, v3
	s_add_u32 s3, s16, 0x1f00000
	s_mov_b64 s[8:9], 0x2800000
	v_cndmask_b32_e32 v4, v2, v4, vcc
	v_lshlrev_b32_e32 v71, 2, v4
	v_xor_b32_e32 v4, 8, v2
	v_cmp_lt_i32_e32 vcc, v4, v3
	s_addc_u32 s24, s17, 0
	v_lshlrev_b32_e32 v1, 2, v1
	v_cndmask_b32_e32 v4, v2, v4, vcc
	v_lshlrev_b32_e32 v72, 2, v4
	v_xor_b32_e32 v4, 16, v2
	v_cmp_lt_i32_e32 vcc, v4, v3
	s_lshl_b32 s25, s52, 4
	s_mul_i32 s26, s52, 24
	v_cndmask_b32_e32 v4, v2, v4, vcc
	v_lshlrev_b32_e32 v73, 2, v4
	v_xor_b32_e32 v4, 32, v2
	v_cmp_lt_i32_e32 vcc, v4, v3
	v_lshlrev_b32_e32 v75, 4, v230
	v_mov_b32_e32 v76, 0x358637bd
	v_cndmask_b32_e32 v2, v2, v4, vcc
	v_lshlrev_b32_e32 v74, 2, v2
	v_lshl_add_u64 v[2:3], s[16:17], 0, v[66:67]
	v_lshl_add_u64 v[68:69], v[2:3], 0, s[8:9]
	s_mov_b32 s27, 0x800000
	s_branch .LBB0_87

; #define GAS __attribute__((address_space(1)))
; __device__ __forceinline__ unsigned pk2(float lo, float hi) { return pg8::cvt_pk_bf16(lo, hi); }
; __device__ __forceinline__ void p0_prologue(KArgs A, unsigned char* ws, LAS unsigned char* lds, int vcu, int G, int wave, int lane) {
;     ...
;     for (int m = gw; m < MALL; m += 4 * NGW) {
;         f32x4 v[4][4]; int mr[4]; bool has[4];
; #pragma unroll
;         for (int r = 0; r < 4; ++r) { const int mm = m + r * NGW; has[r] = mm < MALL; mr[r] = has[r] ? mm : m;
;             const float* xr = mr[r] < MP ? A->in.xp + (size_t)mr[r] * DM : A->in.xs + (size_t)(mr[r] - MP) * DM; const GAS f32x4* p = (const GAS f32x4*)xr + lane;
; #pragma unroll
;             for (int j = 0; j < 4; ++j) v[r][j] = p[64 * j]; }
; #pragma unroll
;         for (int r = 0; r < 4; ++r) { float s = 0.f;
; #pragma unroll
;             for (int j = 0; j < 4; ++j) s += (v[r][j][0] * v[r][j][0] + v[r][j][1] * v[r][j][1]) + (v[r][j][2] * v[r][j][2] + v[r][j][3] * v[r][j][3]);
;             s = wave_sum(s);
;             const float rs = rsqrtf(s * (1.0f / DM) + EPSF);
;             if (has[r]) { GAS v2u* o = (GAS v2u*)(XB + (size_t)mr[r] * DM) + lane;
; #pragma unroll
;                 for (int j = 0; j < 4; ++j) o[64 * j] = (v2u){pk2(v[r][j][0] * rs, v[r][j][1] * rs), pk2(v[r][j][2] * rs, v[r][j][3] * rs)};
;                 if (lane == 0) { RSTD1[mr[r]] = 1.0f / rs; RSS[mr[r]] = 0.f; } }
.LBB0_87:
	s_add_i32 s8, s14, 0xffffc000
	s_ashr_i32 s15, s14, 31
	s_cmpk_lt_i32 s14, 0x4000
	s_cselect_b32 s10, s98, s100
	s_cselect_b32 s11, s99, s101
	s_cselect_b32 s9, s15, 0
	s_cselect_b32 s8, s14, s8
	s_lshl_b64 s[8:9], s[8:9], 12
	s_waitcnt lgkmcnt(0)
	s_add_u32 s8, s10, s8
	s_addc_u32 s9, s11, s9
	global_load_dwordx4 v[58:61], v75, s[8:9]
	global_load_dwordx4 v[54:57], v75, s[8:9] offset:1024
	global_load_dwordx4 v[46:49], v75, s[8:9] offset:3072
	global_load_dwordx4 v[62:65], v75, s[8:9] offset:2048
	s_add_i32 s16, s0, s14
	s_cmpk_lt_i32 s16, 0x4200
	s_cselect_b64 s[18:19], -1, 0
	s_and_b64 s[8:9], s[18:19], exec
	s_cselect_b32 s8, s16, s14
	s_ashr_i32 s9, s8, 31
	s_add_i32 s10, s8, 0xffffc000
	s_cmpk_lt_i32 s8, 0x4000
	s_cselect_b32 s8, s8, s10
	s_cselect_b32 s10, s98, s100
	s_cselect_b32 s11, s99, s101
	s_cselect_b32 s9, s9, 0
	s_lshl_b64 s[8:9], s[8:9], 12
	s_waitcnt lgkmcnt(0)
	s_add_u32 s8, s10, s8
	s_addc_u32 s9, s11, s9
	s_add_i32 s17, s0, s16
	s_cmpk_lt_i32 s17, 0x4200
	s_cselect_b64 s[10:11], -1, 0
	s_and_b64 s[20:21], s[10:11], exec
	s_cselect_b32 s20, s17, s14
	s_ashr_i32 s21, s20, 31
	s_add_i32 s22, s20, 0xffffc000
	s_cmpk_lt_i32 s20, 0x4000
	s_cselect_b32 s20, s20, s22
	s_cselect_b32 s22, s98, s100
	s_cselect_b32 s23, s99, s101
	s_cselect_b32 s21, s21, 0
	global_load_dwordx4 v[38:41], v75, s[8:9]
	global_load_dwordx4 v[34:37], v75, s[8:9] offset:1024
	global_load_dwordx4 v[50:53], v75, s[8:9] offset:2048
	global_load_dwordx4 v[42:45], v75, s[8:9] offset:3072
	s_lshl_b64 s[8:9], s[20:21], 12
	s_waitcnt lgkmcnt(0)
	s_add_u32 s20, s22, s8
	s_addc_u32 s21, s23, s9
	s_add_i32 s22, s0, s17
	s_cmpk_lt_i32 s22, 0x4200
	s_cselect_b64 s[8:9], -1, 0
	s_and_b64 s[28:29], s[8:9], exec
	s_cselect_b32 s17, s22, s14
	s_ashr_i32 s23, s17, 31
	s_add_i32 s28, s17, 0xffffc000
	s_cmpk_lt_i32 s17, 0x4000
	s_cselect_b32 s28, s17, s28
	s_cselect_b32 s30, s98, s100
	s_cselect_b32 s31, s99, s101
	s_cselect_b32 s29, s23, 0
	global_load_dwordx4 v[30:33], v75, s[20:21]
	global_load_dwordx4 v[26:29], v75, s[20:21] offset:1024
	global_load_dwordx4 v[22:25], v75, s[20:21] offset:2048
	global_load_dwordx4 v[18:21], v75, s[20:21] offset:3072
	s_lshl_b64 s[20:21], s[28:29], 12
	s_waitcnt lgkmcnt(0)
	s_add_u32 s20, s30, s20
	s_addc_u32 s21, s31, s21
	global_load_dwordx4 v[6:9], v75, s[20:21]
	global_load_dwordx4 v[2:5], v75, s[20:21] offset:1024
	global_load_dwordx4 v[14:17], v75, s[20:21] offset:2048
	global_load_dwordx4 v[10:13], v75, s[20:21] offset:3072
	s_lshl_b64 s[20:21], s[14:15], 11
	s_waitcnt vmcnt(15)
	v_pk_mul_f32 v[78:79], v[60:61], v[60:61]
	v_pk_mul_f32 v[80:81], v[58:59], v[58:59]
	s_waitcnt vmcnt(14)
	v_pk_mul_f32 v[82:83], v[56:57], v[56:57]
	v_pk_mul_f32 v[84:85], v[54:55], v[54:55]
	v_pk_mov_b32 v[88:89], v[80:81], v[78:79] op_sel:[1,0]
	v_mov_b32_e32 v81, v79
	v_pk_mov_b32 v[78:79], v[84:85], v[82:83] op_sel:[1,0]
	v_mov_b32_e32 v85, v83
	s_waitcnt vmcnt(12)
	v_mul_f32_e32 v66, v63, v63
	v_mul_f32_e32 v86, v65, v65
	v_pk_add_f32 v[80:81], v[88:89], v[80:81]
	v_pk_add_f32 v[78:79], v[78:79], v[84:85]
	v_mul_f32_e32 v77, v46, v46
	v_mul_f32_e32 v90, v47, v47
	v_mul_f32_e32 v91, v48, v48
	v_mul_f32_e32 v92, v49, v49
	v_pk_fma_f32 v[82:83], v[62:63], v[62:63], v[66:67] op_sel_hi:[1,1,0]
	v_pk_fma_f32 v[86:87], v[64:65], v[64:65], v[86:87] op_sel_hi:[1,1,0]
	v_pk_add_f32 v[80:81], v[80:81], v[80:81] op_sel:[0,1] op_sel_hi:[1,0]
	v_pk_add_f32 v[78:79], v[78:79], v[78:79] op_sel:[0,1] op_sel_hi:[1,0]
	v_mov_b32_e32 v83, v91
	v_mov_b32_e32 v87, v92
	v_mov_b32_e32 v81, v77
	v_mov_b32_e32 v79, v90
	v_pk_add_f32 v[82:83], v[82:83], v[86:87]
	v_pk_add_f32 v[78:79], v[80:81], v[78:79]
	s_nop 0
	v_pk_add_f32 v[78:79], v[78:79], v[82:83]
	s_nop 0
	v_add_f32_e32 v66, v78, v79
	ds_bpermute_b32 v77, v1, v66
	v_lshl_add_u64 v[78:79], v[68:69], 0, s[20:21]
	s_waitcnt lgkmcnt(0)
	v_add_f32_e32 v66, v66, v77
	ds_bpermute_b32 v77, v70, v66
	s_waitcnt lgkmcnt(0)
	v_add_f32_e32 v66, v66, v77
	ds_bpermute_b32 v77, v71, v66
	s_waitcnt lgkmcnt(0)
	v_add_f32_e32 v66, v66, v77
	ds_bpermute_b32 v77, v72, v66
	s_waitcnt lgkmcnt(0)
	v_add_f32_e32 v66, v66, v77
	ds_bpermute_b32 v77, v73, v66
	s_waitcnt lgkmcnt(0)
	v_add_f32_e32 v66, v66, v77
	ds_bpermute_b32 v77, v74, v66
	s_waitcnt lgkmcnt(0)
	v_add_f32_e32 v66, v66, v77
	v_fmamk_f32 v66, v66, 0x3a800000, v76
	v_mul_f32_e32 v77, 0x4b800000, v66
	v_cmp_gt_f32_e32 vcc, s27, v66
	s_nop 1
	v_cndmask_b32_e32 v66, v66, v77, vcc
	v_rsq_f32_e32 v66, v66
	s_nop 0
	v_mul_f32_e32 v77, 0x45800000, v66
	v_cndmask_b32_e32 v66, v66, v77, vcc
	v_pk_mul_f32 v[58:59], v[58:59], v[66:67] op_sel_hi:[1,0]
	v_pk_mul_f32 v[60:61], v[60:61], v[66:67] op_sel_hi:[1,0]
	v_pk_mul_f32 v[54:55], v[54:55], v[66:67] op_sel_hi:[1,0]
	v_pk_mul_f32 v[56:57], v[56:57], v[66:67] op_sel_hi:[1,0]
	v_pk_mul_f32 v[62:63], v[62:63], v[66:67] op_sel_hi:[1,0]
	v_pk_mul_f32 v[64:65], v[64:65], v[66:67] op_sel_hi:[1,0]
	v_pk_mul_f32 v[46:47], v[46:47], v[66:67] op_sel_hi:[1,0]
	v_pk_mul_f32 v[48:49], v[48:49], v[66:67] op_sel_hi:[1,0]
	v_cvt_pk_bf16_f32 v58, v58, v59
	v_cvt_pk_bf16_f32 v59, v60, v61
	v_cvt_pk_bf16_f32 v54, v54, v55
	v_cvt_pk_bf16_f32 v55, v56, v57
	v_cvt_pk_bf16_f32 v56, v62, v63
	v_cvt_pk_bf16_f32 v57, v64, v65
	v_cvt_pk_bf16_f32 v46, v46, v47
	v_cvt_pk_bf16_f32 v47, v48, v49
	global_store_dwordx2 v[78:79], v[58:59], off
	global_store_dwordx2 v[78:79], v[54:55], off offset:512
	global_store_dwordx2 v[78:79], v[56:57], off offset:1024
	global_store_dwordx2 v[78:79], v[46:47], off offset:1536
	s_and_saveexec_b64 s[20:21], s[6:7]
	s_cbranch_execz .LBB0_89
	v_div_scale_f32 v46, s[28:29], v66, v66, 1.0
	v_rcp_f32_e32 v47, v46
	v_div_scale_f32 v48, vcc, 1.0, v66, 1.0
	s_lshl_b64 s[28:29], s[14:15], 2
	v_fma_f32 v49, -v46, v47, 1.0
	v_fmac_f32_e32 v47, v49, v47
	v_mul_f32_e32 v49, v48, v47
	v_fma_f32 v54, -v46, v49, v48
	v_fmac_f32_e32 v49, v54, v47
	s_add_u32 s30, s1, s28
	v_fma_f32 v46, -v46, v49, v48
	s_addc_u32 s31, s2, s29
	v_div_fmas_f32 v46, v46, v47, v49
	s_add_u32 s28, s3, s28
	v_div_fixup_f32 v46, v46, v66, 1.0
	s_addc_u32 s29, s24, s29
	global_store_dword v67, v46, s[30:31]
	global_store_dword v67, v67, s[28:29]

; #define LAS __attribute__((address_space(3)))
; __device__ __forceinline__ unsigned xb_xcc_id() { return (unsigned)__builtin_amdgcn_s_getreg((3 << 11) | 20) & 0xFu; }
; __device__ __forceinline__ KArgs kargs() { KArgs p = (KArgs)__builtin_amdgcn_kernarg_segment_ptr(); asm volatile("" : "+s"(p)); return p; }
; __global__ void __launch_bounds__(NWAVES * 64, 2) fwd(Args args_unused) {
;     ...
;     { KArgs A = kargs(); unsigned char* ws = A->ws; const float lam = SCAL[0];
;       const bf16* QB = (const bf16*)(ws + WS_QB); const bf16* KB = (const bf16*)(ws + WS_KB); const bf16* VB = (const bf16*)(ws + WS_VB); bf16* MIX = (bf16*)(ws + WS_MIX);
;       gu32* qd = (gu32*)(ws + WS_CTL) + CW_QDEC; gu32* qa = (gu32*)(ws + WS_CTL) + CW_QATT;
;       volatile LAS unsigned* qs = (volatile LAS unsigned*)(lds + MISC_OFF) + 12;
;       const int home = (int)(xb_xcc_id() & 7u);
;       int mode = (bx >> 3) < (NDEC_CU / 8) ? 0 : 1, done = 0, aq = 0;
;       for (;;) {
;         const int qx = (home + aq) & 7;
.LBB0_607:
	s_mov_b64 s[24:25], s[30:31]
	s_load_dwordx2 s[26:27], s[24:25], 0xb8
	s_add_i32 s0, 0, 0x20a00
	v_mov_b32_e32 v1, s0
	v_lshlrev_b32_e32 v3, 3, v0
	v_lshlrev_b32_e32 v5, 10, v66
	s_waitcnt lgkmcnt(0)
	s_add_u32 s0, s26, 0x4a00000
	s_addc_u32 s1, s27, 0
	s_add_u32 s2, s26, 0x5b00000
	s_addc_u32 s3, s27, 0
	s_add_u32 s33, s26, 0x6c00000
	s_addc_u32 s54, s27, 0
	s_add_u32 s30, s26, 0xd200000
	s_addc_u32 s31, s27, 0
	s_add_u32 s55, s26, 0x8000
	s_addc_u32 s56, s27, 0
	s_add_u32 s57, s26, 0xc000
	s_addc_u32 s58, s27, 0
	s_cmpk_gt_i32 s34, 0x57
	s_cselect_b64 s[8:9], -1, 0
	s_mov_b32 s100, 0
	s_add_u32 s34, s26, 0x18000
	v_lshlrev_b32_e32 v7, 4, v177
	v_lshlrev_b32_e32 v8, 4, v0
	ds_read_b32 v174, v1
	s_addc_u32 s35, s27, 0
	v_and_b32_e32 v4, 24, v3
	v_add3_u32 v173, 0, v5, v7
	v_lshlrev_b32_e32 v5, 1, v0
	v_lshlrev_b32_e32 v7, 8, v66
	v_and_b32_e32 v8, 0xc0, v8
	s_add_i32 s53, 0, 0x10000
	v_add3_u32 v7, v8, s53, v7
	v_and_or_b32 v5, v5, 32, v4
	v_and_b32_e32 v194, 15, v0
	v_add_u32_e32 v201, v5, v7
	v_lshrrev_b32_e32 v5, 4, v230
	v_lshlrev_b32_e32 v8, 1, v230
	s_add_u32 s60, s26, 0x1ac00000
	v_lshlrev_b32_e32 v232, 11, v194
	v_cndmask_b32_e64 v1, 0, 1, s[8:9]
	v_mov_b32_e32 v99, 0
	v_and_b32_e32 v8, 32, v8
	v_and_b32_e32 v176, 0x78, v3
	v_mul_u32_u24_e32 v207, 0x210, v5
	v_lshlrev_b32_e32 v178, 10, v5
	s_addc_u32 s61, s27, 0
	v_lshlrev_b32_e32 v196, 3, v5
	v_and_b32_e32 v3, 3, v0
	v_lshlrev_b32_e32 v223, 2, v5
	v_lshlrev_b32_e32 v5, 13, v5
	v_or_b32_e32 v98, 0x8000, v232
	v_writelane_b32 v255, s84, 11
	v_readfirstlane_b32 s28, v1
	v_lshlrev_b32_e32 v2, 9, v230
	v_and_b32_e32 v1, 0x1e00, v23
	v_lshlrev_b32_e32 v6, 9, v177
	v_add3_u32 v203, v7, v4, v8
	s_add_u32 s63, s26, 0x8400
	v_subrev_co_u32_e64 v222, s[10:11], 4, v194
	v_lshlrev_b32_e32 v8, 9, v194
	v_or_b32_e32 v224, 0x800, v3
	v_cmp_gt_u32_e64 s[14:15], 8, v194
	v_or_b32_e32 v226, 1, v223
	v_or_b32_e32 v228, 2, v223
	v_or_b32_e32 v231, 3, v223
	v_or_b32_e32 v200, 0x8000, v5
	v_or_b32_e32 v202, 0x8800, v5
	v_or_b32_e32 v204, 0x9000, v5
	v_or_b32_e32 v206, 0x9800, v5
	v_min_u32_e32 v5, 3, v194
	v_cmp_gt_u32_e64 s[16:17], 16, v230
	v_add_u32_e32 v233, 0x7fe, v3
	v_add_u32_e32 v234, 0x7fd, v3
	v_or_b32_e32 v235, 0x7f0, v3
	v_add_u32_e32 v236, 0x7ef, v3
	v_add_u32_e32 v237, 0x7ee, v3
	v_add_u32_e32 v238, 0x7ed, v3
	v_mov_b64_e32 v[208:209], v[98:99]
	v_lshlrev_b32_e32 v98, 3, v194
	v_sub_u32_e32 v3, v177, v195
	v_writelane_b32 v255, s85, 12
	s_mov_b32 s29, 0
	s_getreg_b32 s59, hwreg(HW_REG_XCC_ID, 0, 4)
	v_cmp_gt_u32_e64 s[8:9], 32, v230
	v_mul_u32_u24_e32 v205, 0x840, v66
	v_mov_b32_e32 v179, v99
	v_or_b32_e32 v180, 0x1000, v178
	v_mov_b32_e32 v181, v99
	v_or_b32_e32 v182, 0x2000, v178
	v_mov_b32_e32 v183, v99
	v_or_b32_e32 v184, 0x3000, v178
	v_mov_b32_e32 v185, v99
	v_or_b32_e32 v186, 0x4000, v178
	v_mov_b32_e32 v187, v99
	v_or_b32_e32 v188, 0x5000, v178
	v_mov_b32_e32 v189, v99
	v_or_b32_e32 v190, 0x6000, v178
	v_mov_b32_e32 v191, v99
	v_or_b32_e32 v192, 0x7000, v178
	v_mov_b32_e32 v193, v99
	s_addc_u32 s82, s27, 0
	v_mov_b32_e32 v197, v99
	v_cmp_gt_u32_e64 s[12:13], 4, v222
	v_min_u32_e32 v225, 3, v223
	v_min_u32_e32 v227, 3, v226
	v_min_u32_e32 v229, 3, v228
	v_lshlrev_b32_e32 v198, 11, v231
	s_and_b64 s[36:37], s[14:15], s[16:17]
	v_lshl_add_u64 v[210:211], s[30:31], 0, v[98:99]
	v_lshlrev_b32_e32 v239, 11, v5
	s_waitcnt lgkmcnt(0)
	v_mov_b32_e32 v175, v174
	v_add_u32_e32 v240, 0xffffffa5, v3
	s_add_i32 s83, 0, 0x20170
	v_lshlrev_b32_e32 v212, 1, v2
	v_lshlrev_b32_e32 v241, 1, v1
	v_lshlrev_b32_e32 v214, 1, v6
	v_lshlrev_b32_e32 v216, 1, v50
	s_mov_b64 s[38:39], 0x80
	v_lshlrev_b32_e32 v218, 1, v4
	s_mov_b64 s[40:41], 0x10000
	s_mov_b64 s[42:43], 0x10080
	s_mov_b64 s[44:45], 0x20000
	s_mov_b64 s[46:47], 0x30000
	s_mov_b64 s[48:49], 0x40000
	v_mov_b32_e32 v242, 0x358637bd
	s_brev_b32 s62, 60
	s_mov_b32 s84, 0x800000
	v_lshlrev_b32_e32 v220, 2, v8
	v_mov_b32_e32 v243, 0x7f
	v_mov_b32_e32 v244, 0x9f
	v_mov_b32_e32 v245, 0xff800000
	v_mbcnt_hi_u32_b32 v1, -1, v163
	v_mov_b32_e32 v246, 0x1800
	s_mov_b32 s85, 0
	s_mov_b32 s86, 0
	s_branch .LBB0_611

; #define LDS_SYNC() do { asm volatile("s_waitcnt lgkmcnt(0)" ::: "memory"); __builtin_amdgcn_s_barrier(); asm volatile("" ::: "memory"); } while (0)
; __global__ void __launch_bounds__(NWAVES * 64, 2) fwd(Args args_unused) {
;     ...
;       for (;;) {
;         const int qx = (home + aq) & 7;
;         if (tid == 0) qs[0] = __hip_atomic_fetch_add(mode == 0 ? qd : qa + 64 * qx, 1u, RLX_AGENT);
;         LDS_SYNC(); const int i = __builtin_amdgcn_readfirstlane((int)qs[0]); LDS_SYNC();
.LBB0_611:
	s_add_i32 s65, s85, s59
	s_and_b32 s66, s65, 7
	s_and_saveexec_b64 s[18:19], s[50:51]
	s_cbranch_execz .LBB0_615
	s_mov_b64 s[22:23], exec
	v_mbcnt_lo_u32_b32 v2, s22, 0
	v_mbcnt_hi_u32_b32 v2, s23, v2
	v_cmp_eq_u32_e32 vcc, 0, v2
	s_and_saveexec_b64 s[20:21], vcc
	s_cbranch_execz .LBB0_614
	s_cmp_eq_u32 s100, 0
	s_cbranch_scc1 .Lq_claim_now
	s_waitcnt vmcnt(0)
	v_mov_b32_e32 v3, v254
	s_mov_b32 s100, 0
	s_branch .LBB0_614
.Lq_claim_now:
	s_lshl_b32 s64, s66, 8
	s_add_u32 s64, s57, s64
	s_addc_u32 s67, s58, 0
	s_cmp_eq_u32 s28, 0
	s_cselect_b32 s69, s56, s67
	s_cselect_b32 s68, s55, s64
	s_bcnt1_i32_b64 s22, s[22:23]
	v_mov_b32_e32 v3, s22
	global_atomic_add v3, v99, v3, s[68:69] sc0

; __device__ __forceinline__ void attn_unit(int b, int h, int qb, const bf16* Q, const bf16* K, const bf16* V, bf16* MIX, LAS unsigned char* lds, const LAS float* BLh, float lam, LAS float* als, gu32* rdy4) {
;     const int tid = threadIdx.x, lane = tid & 63, r32 = lane & 31, hi = lane >> 5; const int wid = __builtin_amdgcn_readfirstlane(tid >> 6), map = wid >> 2, qw = wid & 3;
;     const long rowbase = (long)b * TP; const int q0 = qb * 128;
;     const bf16* Qw = Q + (rowbase + q0 + qw * 32) * 512 + h * 128 + map * 64;
;     const bf16* Kh = K + rowbase * 512 + h * 128; const bf16* Vh = V + rowbase * 512 + h * 128;
;     const unsigned lds0 = (unsigned)(uintptr_t)lds;
;     const bf16* ksrc0 = Kh + (long)lane * 512 + (wid >> 3) * 64 + (wid & 7) * 8;
;     const bf16* ksrc1 = Kh + (long)lane * 512 + 64 + (wid & 7) * 8;
;     const bf16* vsrc0 = Vh + (long)(16 * (wid & 3) + (lane >> 2)) * 512 + (wid >> 2) * 32 + (lane & 3) * 8;
;     const bf16* vsrc1 = Vh + (long)(16 * (wid & 3) + (lane >> 2)) * 512 + (2 + (wid >> 2)) * 32 + (lane & 3) * 8;
;     ...
;     const int NT = 2 * qb + 2;
;     bf16x8 qr[4];
; #pragma unroll
;     for (int d0 = 0; d0 < 4; ++d0) qr[d0] = *(const bf16x8*)(Qw + (long)r32 * 512 + d0 * 16 + hi * 8);
;     asm volatile("s_waitcnt vmcnt(0)" ::: "memory");
;     ADMA(0, 0); ADMA(1, 1); if (NT > 2) { ADMA(2, 2); }
;     f32x16 o[4];
; #pragma unroll
;     for (int d = 0; d < 4; ++d)
; #pragma unroll
;         for (int r = 0; r < 16; ++r) o[d][r] = 0.f;
;     float lsum = 0.f;
;     const float cfar = BLh[127];
; __global__ void __launch_bounds__(NWAVES * 64, 2) fwd(Args args_unused) {
;     ...
;         LDS_SYNC(); const int i = __builtin_amdgcn_readfirstlane((int)qs[0]); LDS_SYNC();
;         if (mode == 0) {
;           if (i >= 512 * REP_Q) { if (++done == 2) break; mode = 1; continue; }
;           dec::decode_unit(i % 512, A->in.ck, A->in.cv, A->in.pt, QB, A->out + O_KS, A->out + O_VS, MIX, lds, BL, lam, (float*)(ws + WS_DPART), (gu32*)(ws + WS_CTL) + CW_DCNT, MIX, (gu32*)(ws + WS_CTL) + CW_RDY4);
;         } else {
;           if (i >= 64 * REP_Q) { if (++aq == 8) { aq = 0; if (++done == 2) break; mode = 0; } continue; }
;           const int bh = qx, qb = 63 - (i & 63);
;           att::attn_unit(bh >> 2, bh & 3, qb, QB, KB, VB, MIX, lds, BL + (bh & 3) * 128, lam, (LAS float*)(lds + ALS_OFF), (gu32*)(ws + WS_CTL) + CW_RDY4);
.LBB0_615:
	s_or_b64 exec, exec, s[18:19]
	s_waitcnt lgkmcnt(0)
	s_barrier
	v_mov_b32_e32 v2, s83
	ds_read_b32 v2, v2
	s_waitcnt lgkmcnt(0)
	s_barrier
	s_cmp_lg_u32 s28, 0
	s_waitcnt lgkmcnt(0)
	v_readfirstlane_b32 s64, v2
	s_cbranch_scc0 .LBB0_627
	s_cmp_lt_i32 s64, 64
	s_mov_b64 s[18:19], -1
	s_cbranch_scc0 .LBB0_653
	s_and_b32 s22, s64, 63
	s_xor_b32 s73, s22, 63
	s_lshr_b32 s20, s66, 2
	v_readfirstlane_b32 s68, v0
	s_and_b32 s75, s65, 3
	s_bfe_u32 s70, s68, 0x20006
	s_lshl_b32 s65, s20, 13
	s_lshl_b32 s66, s73, 7
	s_or_b32 s18, s66, s65
	s_lshl_b32 s74, s70, 5
	s_or_b32 s67, s74, s18
	s_lshr_b32 s71, s68, 6
	s_lshr_b32 s69, s68, 8
	s_lshl_b32 s18, s67, 10
	s_add_u32 s18, s0, s18
	s_addc_u32 s19, s1, 0
	s_lshl_b32 s21, s75, 8
	s_add_u32 s18, s18, s21
	s_addc_u32 s19, s19, 0
	s_lshl_b32 s28, s69, 6
	s_lshl_b32 s23, s69, 7
	s_add_u32 s18, s18, s23
	s_addc_u32 s19, s19, 0
	v_mov_b32_e32 v215, v99
	v_lshl_add_u64 v[2:3], s[18:19], 0, v[214:215]
	v_mov_b32_e32 v217, v99
	v_lshl_add_u64 v[248:249], v[2:3], 0, v[216:217]
	s_lshl_b32 s20, s20, 23
	s_add_u32 s18, s2, s20
	s_addc_u32 s19, s3, 0
	s_add_u32 s18, s18, s21
	s_addc_u32 s19, s19, 0
	s_add_u32 s20, s33, s20
	s_addc_u32 s23, s54, 0
	s_add_u32 s20, s20, s21
	s_addc_u32 s21, s23, 0
	v_mov_b32_e32 v213, v99
	v_lshl_or_b32 v98, s70, 14, v241
	v_lshl_add_u64 v[2:3], s[18:19], 0, v[212:213]
	v_lshl_add_u64 v[4:5], s[20:21], 0, v[98:99]
	s_lshr_b32 s18, s68, 2
	v_lshl_add_u64 v[4:5], v[4:5], 0, s[28:29]
	s_and_b32 s28, s18, 0x3fffff80
	v_lshl_add_u64 v[6:7], v[2:3], 0, s[28:29]
	s_and_b32 s28, s18, 0x70
	v_lshl_add_u64 v[34:35], v[6:7], 0, s[28:29]
	v_lshl_add_u64 v[2:3], v[2:3], 0, s[28:29]
	s_waitcnt vmcnt(0)
	s_lshl_b32 s28, s71, 10
	s_add_i32 s76, s28, 0
	s_mov_b32 s18, m0
	s_mov_b32 m0, s76
	s_nop 0
	global_load_lds_dwordx4 v[34:35], off
	s_mov_b32 m0, s18
	v_lshl_add_u64 v[36:37], v[2:3], 0, s[38:39]
	v_mov_b32_e32 v219, v99
	s_add_i32 s18, s76, 0x2000
	s_mov_b32 s19, m0
	s_mov_b32 m0, s18
	s_nop 0
	global_load_lds_dwordx4 v[36:37], off
	s_mov_b32 m0, s19
	v_lshl_add_u64 v[38:39], v[4:5], 0, v[218:219]
	s_add_i32 s18, s76, 0x10000
	s_mov_b32 s19, m0
	s_mov_b32 m0, s18
	s_nop 0
	global_load_lds_dwordx4 v[38:39], off
	s_mov_b32 m0, s19
	v_lshl_add_u64 v[40:41], v[38:39], 0, s[38:39]
	s_add_i32 s18, s76, 0x12000
	s_mov_b32 s19, m0
	s_mov_b32 m0, s18
	s_nop 0
	global_load_lds_dwordx4 v[40:41], off
	s_mov_b32 m0, s19
	v_lshl_add_u64 v[4:5], v[34:35], 0, s[40:41]
	s_add_i32 s18, s76, 0x4000
	s_mov_b32 s19, m0
	s_mov_b32 m0, s18
	s_nop 0
	global_load_lds_dwordx4 v[4:5], off
	s_mov_b32 m0, s19
	v_lshl_add_u64 v[2:3], v[2:3], 0, s[42:43]
	s_add_i32 s18, s76, 0x6000
	s_mov_b32 s19, m0
	s_mov_b32 m0, s18
	s_nop 0
	global_load_lds_dwordx4 v[2:3], off
	s_mov_b32 m0, s19
	v_lshl_add_u64 v[2:3], v[38:39], 0, s[40:41]
	s_add_i32 s18, s76, 0x14000
	s_mov_b32 s19, m0
	s_mov_b32 m0, s18
	s_nop 0
	global_load_lds_dwordx4 v[2:3], off
	s_mov_b32 m0, s19
	v_lshl_add_u64 v[2:3], v[38:39], 0, s[42:43]
	s_add_i32 s18, s76, 0x16000
	s_mov_b32 s19, m0
	s_mov_b32 m0, s18
	s_nop 0
	global_load_lds_dwordx4 v[2:3], off
	s_mov_b32 m0, s19
	s_cmp_lg_u32 s22, 63
	s_cselect_b64 s[20:21], -1, 0
	s_cmp_eq_u32 s22, 63
	s_cbranch_scc1 .LBB0_619
	v_lshl_add_u64 v[2:3], v[34:35], 0, s[44:45]
	s_add_i32 s18, s76, 0x8000
	s_mov_b32 s19, m0
	s_mov_b32 m0, s18
	s_nop 0
	global_load_lds_dwordx4 v[2:3], off
	s_mov_b32 m0, s19
	v_lshl_add_u64 v[2:3], v[36:37], 0, s[44:45]
	s_add_i32 s18, s76, 0xa000
	s_mov_b32 s19, m0
	s_mov_b32 m0, s18
	s_nop 0
	global_load_lds_dwordx4 v[2:3], off
	s_mov_b32 m0, s19
	v_lshl_add_u64 v[2:3], v[38:39], 0, s[44:45]
	s_add_i32 s18, s76, 0x18000
	s_mov_b32 s19, m0
	s_mov_b32 m0, s18
	s_nop 0
	global_load_lds_dwordx4 v[2:3], off
	s_mov_b32 m0, s19
	v_lshl_add_u64 v[2:3], v[40:41], 0, s[44:45]
	s_add_i32 s18, s76, 0x1a000
	s_mov_b32 s19, m0
	s_mov_b32 m0, s18
	s_nop 0
	global_load_lds_dwordx4 v[2:3], off
	s_mov_b32 m0, s19
.LBB0_619:
	global_load_dwordx4 v[100:103], v[248:249], off
	global_load_dwordx4 v[104:107], v[248:249], off offset:32
	global_load_dwordx4 v[108:111], v[248:249], off offset:64
	global_load_dwordx4 v[112:115], v[248:249], off offset:96
	s_lshl_b32 s18, s75, 9
	s_add_i32 s72, s18, 0
	s_add_i32 s72, s72, 0x20200
	v_mov_b32_e32 v2, s72
	ds_read_b32 v98, v2 offset:508
	v_cndmask_b32_e64 v2, 0, 1, s[20:21]
	v_cmp_ne_u32_e64 s[18:19], 1, v2
	s_andn2_b64 vcc, exec, s[20:21]
	s_mov_b64 s[22:23], -1
	s_cbranch_vccnz .LBB0_621
	s_waitcnt vmcnt(0) lgkmcnt(0)
	s_barrier
	s_mov_b64 s[22:23], 0
.LBB0_621:
	s_andn2_b64 vcc, exec, s[22:23]
	s_cbranch_vccnz .LBB0_623
	s_waitcnt vmcnt(0) lgkmcnt(0)
	s_barrier

; #define LAS __attribute__((address_space(3)))
; __device__ __forceinline__ int crow(int r, int hi) { return (r & 3) + 8 * (r >> 2) + 4 * hi; }
; __device__ __forceinline__ void attn_unit(int b, int h, int qb, const bf16* Q, const bf16* K, const bf16* V, bf16* MIX, LAS unsigned char* lds, const LAS float* BLh, float lam, LAS float* als, gu32* rdy4) {
;     ...
;     { const int vb = (int)(lds0 + L_V + pslot * SLOT) + ((lane >> 4) & 1) * 32 + (lane & 3) * 8 + (4 * hi + ((lane & 15) >> 2)) * 64;
;       ATT_PVALL(false); }
;     ...
;     { auto rr = __builtin_amdgcn_permlane32_swap(__float_as_uint(lsum), __float_as_uint(lsum), false, false); lsum = __uint_as_float(rr[0]) + __uint_as_float(rr[1]); }
;     LAS float* myl = als + wid * 32;
;     if (hi == 0) myl[r32] = lsum;
;     asm volatile("s_waitcnt vmcnt(0) lgkmcnt(0)\n\ts_barrier" ::: "memory");
;     float rl[16];
; #pragma unroll
;     for (int r = 0; r < 16; ++r) rl[r] = __builtin_amdgcn_rcpf(myl[crow(r, hi)]);
; __global__ void __launch_bounds__(NWAVES * 64, 2) fwd(Args args_unused) {
;     ...
;         if (tid == 0) qs[0] = __hip_atomic_fetch_add(mode == 0 ? qd : qa + 64 * qx, 1u, RLX_AGENT);
.LBB0_643:
	v_add_u32_e32 v98, s75, v203
	ds_read_b64_tr_b16 v[66:67],v98 offset:0
	ds_read_b64_tr_b16 v[68:69],v98 offset:512
	ds_read_b64_tr_b16 v[70:71],v98 offset:4096
	ds_read_b64_tr_b16 v[72:73],v98 offset:4608
	ds_read_b64_tr_b16 v[74:75],v98 offset:8192
	ds_read_b64_tr_b16 v[76:77],v98 offset:8704
	ds_read_b64_tr_b16 v[78:79],v98 offset:12288
	ds_read_b64_tr_b16 v[80:81],v98 offset:12800
	ds_read_b64_tr_b16 v[82:83],v98 offset:1024
	ds_read_b64_tr_b16 v[84:85],v98 offset:1536
	ds_read_b64_tr_b16 v[86:87],v98 offset:5120
	ds_read_b64_tr_b16 v[88:89],v98 offset:5632
	ds_read_b64_tr_b16 v[90:91],v98 offset:9216
	ds_read_b64_tr_b16 v[92:93],v98 offset:9728
	ds_read_b64_tr_b16 v[94:95],v98 offset:13312
	ds_read_b64_tr_b16 v[96:97],v98 offset:13824
	s_nop 0
	s_waitcnt lgkmcnt(8)
	s_lshl_b32 s18, s71, 7
	v_mfma_f32_32x32x16_bf16 v[50:65], v[128:131], v[66:69], v[50:65]
	ds_read_b64_tr_b16 v[66:67],v98 offset:2048
	ds_read_b64_tr_b16 v[68:69],v98 offset:2560
	s_add_i32 s21, s18, 0
	s_add_i32 s21, s21, 0x21a80
	v_mfma_f32_32x32x16_bf16 v[34:49], v[128:131], v[70:73], v[34:49]
	ds_read_b64_tr_b16 v[70:71],v98 offset:6144
	ds_read_b64_tr_b16 v[72:73],v98 offset:6656
	v_mfma_f32_32x32x16_bf16 v[18:33], v[128:131], v[74:77], v[18:33]
	ds_read_b64_tr_b16 v[74:75],v98 offset:10240
	ds_read_b64_tr_b16 v[76:77],v98 offset:10752
	v_mfma_f32_32x32x16_bf16 v[2:17], v[128:131], v[78:81], v[2:17]
	ds_read_b64_tr_b16 v[78:79],v98 offset:14336
	ds_read_b64_tr_b16 v[80:81],v98 offset:14848
	s_waitcnt lgkmcnt(8)
	s_nop 0
	v_mfma_f32_32x32x16_bf16 v[50:65], v[124:127], v[82:85], v[50:65]
	ds_read_b64_tr_b16 v[82:83],v98 offset:3072
	ds_read_b64_tr_b16 v[84:85],v98 offset:3584
	v_mfma_f32_32x32x16_bf16 v[34:49], v[124:127], v[86:89], v[34:49]
	ds_read_b64_tr_b16 v[86:87],v98 offset:7168
	ds_read_b64_tr_b16 v[88:89],v98 offset:7680
	v_mfma_f32_32x32x16_bf16 v[18:33], v[124:127], v[90:93], v[18:33]
	ds_read_b64_tr_b16 v[90:91],v98 offset:11264
	ds_read_b64_tr_b16 v[92:93],v98 offset:11776
	v_mfma_f32_32x32x16_bf16 v[2:17], v[124:127], v[94:97], v[2:17]
	ds_read_b64_tr_b16 v[94:95],v98 offset:15360
	ds_read_b64_tr_b16 v[96:97],v98 offset:15872
	s_waitcnt lgkmcnt(8)
	s_nop 0
	s_waitcnt lgkmcnt(0)
	v_mfma_f32_32x32x16_bf16 v[50:65], v[120:123], v[66:69], v[50:65]
	v_mov_b32_e32 v66, v141
	s_nop 1
	v_permlane32_swap_b32_e32 v141, v66
	v_mfma_f32_32x32x16_bf16 v[34:49], v[120:123], v[70:73], v[34:49]
	v_mfma_f32_32x32x16_bf16 v[18:33], v[120:123], v[74:77], v[18:33]
	v_mfma_f32_32x32x16_bf16 v[2:17], v[120:123], v[78:81], v[2:17]
	v_mfma_f32_32x32x16_bf16 v[50:65], v[116:119], v[82:85], v[50:65]
	v_mfma_f32_32x32x16_bf16 v[34:49], v[116:119], v[86:89], v[34:49]
	v_mfma_f32_32x32x16_bf16 v[18:33], v[116:119], v[90:93], v[18:33]
	v_mfma_f32_32x32x16_bf16 v[2:17], v[116:119], v[94:97], v[2:17]
	s_and_saveexec_b64 s[18:19], s[8:9]
	v_add_f32_e32 v66, v141, v66
	v_lshl_add_u32 v67, v177, 2, s21
	ds_write_b32 v67, v66
	s_or_b64 exec, exec, s[18:19]
	s_waitcnt vmcnt(0) lgkmcnt(0)
	s_barrier
	s_mov_b64 vcc, exec
	s_and_b64 exec, exec, s[50:51]
	s_add_i32 s101, s85, s59
	s_and_b32 s101, s101, 7
	s_lshl_b32 s101, s101, 8
	s_add_u32 s98, s57, s101
	s_addc_u32 s99, s58, 0
	v_mov_b32_e32 v253, 0
	v_mov_b32_e32 v254, 1
	global_atomic_add v254, v253, v254, s[98:99] sc0
	s_mov_b64 exec, vcc
	s_mov_b32 s100, 1
	v_add_u32_e32 v74, s21, v199
	ds_read_b128 v[66:69], v74
	ds_read_b128 v[70:73], v74 offset:32
	s_mulk_i32 s70, 0x4400
	s_add_i32 s18, s70, 0
	ds_read_b128 v[84:87], v74 offset:96
	s_waitcnt lgkmcnt(2)
	v_rcp_f32_e32 v82, v66
	v_rcp_f32_e32 v80, v67
	v_rcp_f32_e32 v79, v68
	v_rcp_f32_e32 v78, v69
	ds_read_b128 v[66:69], v74 offset:64
	s_waitcnt lgkmcnt(2)
	v_rcp_f32_e32 v77, v70
	v_rcp_f32_e32 v81, v71
	v_rcp_f32_e32 v76, v72
	v_rcp_f32_e32 v75, v73
	s_waitcnt lgkmcnt(0)
	v_rcp_f32_e32 v73, v66
	v_rcp_f32_e32 v72, v67
	v_rcp_f32_e32 v71, v68
	v_rcp_f32_e32 v70, v69
	v_rcp_f32_e32 v69, v84
	v_rcp_f32_e32 v68, v85
	v_rcp_f32_e32 v67, v86
	v_rcp_f32_e32 v66, v87
	s_cmp_lg_u32 s69, 1
	v_lshl_add_u32 v74, v230, 2, s18
	s_cbranch_scc1 .LBB0_647
; #define LAS __attribute__((address_space(3)))
; __device__ __forceinline__ void attn_unit(int b, int h, int qb, const bf16* Q, const bf16* K, const bf16* V, bf16* MIX, LAS unsigned char* lds, const LAS float* BLh, float lam, LAS float* als, gu32* rdy4) {
;     ...
;     LAS float* stg = (LAS float*)(lds + L_STG + qw * STG_BYTES);
;     if (map == 1) {
; #pragma unroll
;         for (int d = 0; d < 4; ++d)
; #pragma unroll
;             for (int r = 0; r < 16; ++r) stg[(d * 16 + r) * 64 + lane] = o[d][r] * rl[r];
;     }
	v_mul_f32_e32 v83, v50, v82
	v_mul_f32_e32 v84, v51, v80
	ds_write2st64_b32 v74, v83, v84 offset1:1
	v_mul_f32_e32 v83, v52, v79
	v_mul_f32_e32 v84, v53, v78
	ds_write2st64_b32 v74, v83, v84 offset0:2 offset1:3
	v_mul_f32_e32 v83, v54, v77
	v_mul_f32_e32 v84, v55, v81
	ds_write2st64_b32 v74, v83, v84 offset0:4 offset1:5
	v_mul_f32_e32 v83, v56, v76
	v_mul_f32_e32 v84, v57, v75
	ds_write2st64_b32 v74, v83, v84 offset0:6 offset1:7
	v_mul_f32_e32 v83, v58, v73
	v_mul_f32_e32 v84, v59, v72
	ds_write2st64_b32 v74, v83, v84 offset0:8 offset1:9
	v_mul_f32_e32 v83, v60, v71
	v_mul_f32_e32 v84, v61, v70
	ds_write2st64_b32 v74, v83, v84 offset0:10 offset1:11
	v_mul_f32_e32 v83, v62, v69
	v_mul_f32_e32 v84, v63, v68
	ds_write2st64_b32 v74, v83, v84 offset0:12 offset1:13
	v_mul_f32_e32 v83, v64, v67
	v_mul_f32_e32 v84, v65, v66
	ds_write2st64_b32 v74, v83, v84 offset0:14 offset1:15
	v_mul_f32_e32 v83, v34, v82
	v_mul_f32_e32 v84, v35, v80
	ds_write2st64_b32 v74, v83, v84 offset0:16 offset1:17
	v_mul_f32_e32 v83, v36, v79
	v_mul_f32_e32 v84, v37, v78
	ds_write2st64_b32 v74, v83, v84 offset0:18 offset1:19
	v_mul_f32_e32 v83, v38, v77
	v_mul_f32_e32 v84, v39, v81
	ds_write2st64_b32 v74, v83, v84 offset0:20 offset1:21
	v_mul_f32_e32 v83, v40, v76
	v_mul_f32_e32 v84, v41, v75
	ds_write2st64_b32 v74, v83, v84 offset0:22 offset1:23
	v_mul_f32_e32 v83, v42, v73
	v_mul_f32_e32 v84, v43, v72
	ds_write2st64_b32 v74, v83, v84 offset0:24 offset1:25
	v_mul_f32_e32 v83, v44, v71
	v_mul_f32_e32 v84, v45, v70
	ds_write2st64_b32 v74, v83, v84 offset0:26 offset1:27
	v_mul_f32_e32 v83, v46, v69
	v_mul_f32_e32 v84, v47, v68
	ds_write2st64_b32 v74, v83, v84 offset0:28 offset1:29
	v_mul_f32_e32 v83, v48, v67
	v_mul_f32_e32 v84, v49, v66
	ds_write2st64_b32 v74, v83, v84 offset0:30 offset1:31
	v_mul_f32_e32 v83, v18, v82
	v_mul_f32_e32 v84, v19, v80
	ds_write2st64_b32 v74, v83, v84 offset0:32 offset1:33
	v_mul_f32_e32 v83, v20, v79
	v_mul_f32_e32 v84, v21, v78
	ds_write2st64_b32 v74, v83, v84 offset0:34 offset1:35
	v_mul_f32_e32 v83, v22, v77
	v_mul_f32_e32 v84, v23, v81
	ds_write2st64_b32 v74, v83, v84 offset0:36 offset1:37
	v_mul_f32_e32 v83, v24, v76
	v_mul_f32_e32 v84, v25, v75
	ds_write2st64_b32 v74, v83, v84 offset0:38 offset1:39
	v_mul_f32_e32 v83, v26, v73
	v_mul_f32_e32 v84, v27, v72
	ds_write2st64_b32 v74, v83, v84 offset0:40 offset1:41
	v_mul_f32_e32 v83, v28, v71
	v_mul_f32_e32 v84, v29, v70
	ds_write2st64_b32 v74, v83, v84 offset0:42 offset1:43
	v_mul_f32_e32 v83, v30, v69
	v_mul_f32_e32 v84, v31, v68
	ds_write2st64_b32 v74, v83, v84 offset0:44 offset1:45
	v_mul_f32_e32 v83, v32, v67
	v_mul_f32_e32 v84, v33, v66
	ds_write2st64_b32 v74, v83, v84 offset0:46 offset1:47
	v_mul_f32_e32 v83, v2, v82
	v_mul_f32_e32 v84, v3, v80
	ds_write2st64_b32 v74, v83, v84 offset0:48 offset1:49
	v_mul_f32_e32 v83, v4, v79
	v_mul_f32_e32 v84, v5, v78
	ds_write2st64_b32 v74, v83, v84 offset0:50 offset1:51
	v_mul_f32_e32 v83, v6, v77
	v_mul_f32_e32 v84, v7, v81
	ds_write2st64_b32 v74, v83, v84 offset0:52 offset1:53
	v_mul_f32_e32 v83, v8, v76
	v_mul_f32_e32 v84, v9, v75
	ds_write2st64_b32 v74, v83, v84 offset0:54 offset1:55
	v_mul_f32_e32 v83, v10, v73
	v_mul_f32_e32 v84, v11, v72
	ds_write2st64_b32 v74, v83, v84 offset0:56 offset1:57
	v_mul_f32_e32 v83, v12, v71
	v_mul_f32_e32 v84, v13, v70
	ds_write2st64_b32 v74, v83, v84 offset0:58 offset1:59
	v_mul_f32_e32 v83, v14, v69
	v_mul_f32_e32 v84, v15, v68
	ds_write2st64_b32 v74, v83, v84 offset0:60 offset1:61
	v_mul_f32_e32 v83, v16, v67
	v_mul_f32_e32 v84, v17, v66
	ds_write2st64_b32 v74, v83, v84 offset0:62 offset1:63

; #define MFMA16(a, b, c) __builtin_amdgcn_mfma_f32_16x16x32_bf16((a), (b), (c), 0, 0, 0)
; __device__ __forceinline__ bf16x8 cvt8(f32x4 a, f32x4 b) { v4u w = {pk2(a[0], a[1]), pk2(a[2], a[3]), pk2(b[0], b[1]), pk2(b[2], b[3])}; return __builtin_bit_cast(bf16x8, w); }
; #define DEC_LOADV(VB_, NEW_) do { _Pragma("unroll") for (int j = 0; j < 8; ++j) { int key_ = (j < 4) ? vkey0 + j : 16 + vkey0 + (j - 4); if (NEW_) key_ = key_ > 3 ? 3 : key_; \
;         _Pragma("unroll") for (int hf = 0; hf < 2; ++hf) vr[j][hf] = *(const f32x4*)((VB_) + (size_t)key_ * 512 + 64 * hf + 4 * n); } } while (0)
; __device__ __forceinline__ void decode_unit(int item, const float* ck, const float* cv, const int* pt, const bf16* QB, const float* ksamp, const float* vsamp, bf16* MIX_unused_, LAS unsigned char* lds, const LAS float* BL, float lam, float* PART, gu32* dcnt, bf16* MIX, gu32* rdy4) {
;     ...
;     for (int i = 0; i < NIT; ++i) {
;         __builtin_amdgcn_sched_barrier(0);
;         DEC_LOADV(vbase, isnew);
;         __builtin_amdgcn_sched_barrier(0);
;         f32x4 s[2];
; #pragma unroll
;         for (int sub = 0; sub < 2; ++sub) {
;             s[sub] = (f32x4){0.f, 0.f, 0.f, 0.f};
; #pragma unroll
;             for (int mp = 0; mp < 2; ++mp)
; #pragma unroll
;                 for (int ks = 0; ks < 2; ++ks) s[sub] = MFMA16(cvt8(kr[sub][mp][ks][0], kr[sub][mp][ks][1]), qfl[(mp * 2 + ks) * 64], s[sub]);
;         }
;         const int key0c = key0; const bool isnewc = isnew;
;         __builtin_amdgcn_sched_barrier(0);
;         const float* vb_cur = vbase;
;         if (i + 1 < NIT) { DEC_BASES(i + 1, kbase, vbase, key0, isnew); DEC_LOADK(kbase, isnew); }
;         __builtin_amdgcn_sched_barrier(0);
;         (void)vb_cur;
;         f32x4 p[2], bvs[2];
; #pragma unroll
;         for (int sub = 0; sub < 2; ++sub)
; #pragma unroll
;             for (int r = 0; r < 4; ++r) { const int dist = PAST + tok - (key0c + 16 * sub + 4 * q + r); bvs[sub][r] = BLh[dist > 127 ? 127 : (dist < 0 ? 0 : dist)]; }
; __global__ void __launch_bounds__(NWAVES * 64, 2) fwd(Args args_unused) {
;     ...
;         if (tid == 0) qs[0] = __hip_atomic_fetch_add(mode == 0 ? qd : qa + 64 * qx, 1u, RLX_AGENT);
.LBB0_670:
	s_mov_b64 vcc, exec
	s_and_b64 exec, exec, s[50:51]
	s_mov_b32 s98, s55
	s_mov_b32 s99, s56
	v_mov_b32_e32 v253, 0
	v_mov_b32_e32 v254, 1
	global_atomic_add v254, v253, v254, s[98:99] sc0
	s_mov_b64 exec, vcc
	s_mov_b32 s100, 1
	v_lshl_add_u64 v[128:129], s[78:79], 0, v[98:99]
	v_cndmask_b32_e64 v98, v223, v225, s[74:75]
	v_lshlrev_b32_e32 v98, 11, v98
	v_lshl_add_u64 v[100:101], v[128:129], 0, v[98:99]
	v_cndmask_b32_e64 v98, v226, v227, s[74:75]
	v_lshlrev_b32_e32 v98, 11, v98
	v_lshl_add_u64 v[104:105], v[128:129], 0, v[98:99]
	v_cndmask_b32_e64 v98, v228, v229, s[74:75]
	v_lshlrev_b32_e32 v98, 11, v98
	v_lshl_add_u64 v[108:109], v[128:129], 0, v[98:99]
	v_cndmask_b32_e64 v98, v198, v246, s[74:75]
	v_lshl_add_u64 v[112:113], v[128:129], 0, v[98:99]
	v_cndmask_b32_e64 v98, v200, v246, s[74:75]
	v_lshl_add_u64 v[116:117], v[128:129], 0, v[98:99]
	v_cndmask_b32_e64 v98, v202, v246, s[74:75]
	v_lshl_add_u64 v[120:121], v[128:129], 0, v[98:99]
	v_cndmask_b32_e64 v98, v204, v246, s[74:75]
	v_lshl_add_u64 v[124:125], v[128:129], 0, v[98:99]
	v_cndmask_b32_e64 v98, v206, v246, s[74:75]
	v_lshl_add_u64 v[128:129], v[128:129], 0, v[98:99]
	global_load_dwordx4 v[132:135], v[100:101], off
	s_nop 0
	global_load_dwordx4 v[100:103], v[100:101], off offset:256
	s_nop 0
	global_load_dwordx4 v[136:139], v[104:105], off
	s_nop 0
	global_load_dwordx4 v[104:107], v[104:105], off offset:256
	s_nop 0
	global_load_dwordx4 v[140:143], v[108:109], off
	s_nop 0
	global_load_dwordx4 v[108:111], v[108:109], off offset:256
	s_nop 0
	global_load_dwordx4 v[144:147], v[112:113], off
	s_nop 0
	global_load_dwordx4 v[112:115], v[112:113], off offset:256
	s_nop 0
	global_load_dwordx4 v[148:151], v[116:117], off
	s_nop 0
	global_load_dwordx4 v[116:119], v[116:117], off offset:256
	s_nop 0
	global_load_dwordx4 v[152:155], v[120:121], off
	s_nop 0
	global_load_dwordx4 v[120:123], v[120:121], off offset:256
	s_nop 0
	global_load_dwordx4 v[156:159], v[124:125], off
	s_nop 0
	global_load_dwordx4 v[124:127], v[124:125], off offset:256
	s_nop 0
	global_load_dwordx4 v[160:163], v[128:129], off
	s_nop 0
	global_load_dwordx4 v[128:131], v[128:129], off offset:256
	s_waitcnt vmcnt(30)
	v_cvt_pk_bf16_f32 v62, v62, v63
	v_cvt_pk_bf16_f32 v63, v64, v65
	v_cvt_pk_bf16_f32 v64, v58, v59
	v_cvt_pk_bf16_f32 v65, v60, v61
	ds_read_b128 v[58:61], v213 offset:40960
	ds_read_b128 v[164:167], v213 offset:41984
	s_waitcnt vmcnt(28)
	v_cvt_pk_bf16_f32 v54, v54, v55
	v_cvt_pk_bf16_f32 v55, v56, v57
	v_cvt_pk_bf16_f32 v56, v50, v51
	v_cvt_pk_bf16_f32 v57, v52, v53
	s_waitcnt lgkmcnt(1)
	v_mfma_f32_16x16x32_bf16 v[62:65], v[62:65], v[58:61], 0
	s_waitcnt vmcnt(26)
	v_cvt_pk_bf16_f32 v46, v46, v47
	v_cvt_pk_bf16_f32 v47, v48, v49
	v_cvt_pk_bf16_f32 v48, v42, v43
	v_cvt_pk_bf16_f32 v49, v44, v45
	s_waitcnt lgkmcnt(0)
	v_mfma_f32_16x16x32_bf16 v[50:53], v[54:57], v[164:167], v[62:65]
	ds_read_b128 v[42:45], v213 offset:43008
	ds_read_b128 v[54:57], v213 offset:44032
	s_waitcnt vmcnt(24)
	v_cvt_pk_bf16_f32 v38, v38, v39
	v_cvt_pk_bf16_f32 v39, v40, v41
	v_cvt_pk_bf16_f32 v40, v34, v35
	v_cvt_pk_bf16_f32 v41, v36, v37
	s_waitcnt lgkmcnt(1)
	v_mfma_f32_16x16x32_bf16 v[46:49], v[46:49], v[42:45], v[50:53]
	s_waitcnt lgkmcnt(0)
	v_mfma_f32_16x16x32_bf16 v[34:37], v[38:41], v[54:57], v[46:49]
	s_waitcnt vmcnt(22)
	v_cvt_pk_bf16_f32 v38, v94, v95
	v_cvt_pk_bf16_f32 v39, v96, v97
	v_cvt_pk_bf16_f32 v40, v86, v87
	v_cvt_pk_bf16_f32 v41, v88, v89
	s_waitcnt vmcnt(20)
	v_cvt_pk_bf16_f32 v46, v90, v91
	v_cvt_pk_bf16_f32 v47, v92, v93
	v_cvt_pk_bf16_f32 v48, v82, v83
	v_cvt_pk_bf16_f32 v49, v84, v85
	v_mfma_f32_16x16x32_bf16 v[38:41], v[38:41], v[58:61], 0
	s_nop 0
	v_mfma_f32_16x16x32_bf16 v[38:41], v[46:49], v[164:167], v[38:41]
	s_waitcnt vmcnt(18)
	v_cvt_pk_bf16_f32 v46, v70, v71
	v_cvt_pk_bf16_f32 v47, v72, v73
	v_cvt_pk_bf16_f32 v48, v78, v79
	v_cvt_pk_bf16_f32 v49, v80, v81
	s_nop 1
	v_mfma_f32_16x16x32_bf16 v[38:41], v[46:49], v[42:45], v[38:41]
	s_waitcnt vmcnt(16)
	v_cvt_pk_bf16_f32 v42, v66, v67
	v_cvt_pk_bf16_f32 v43, v68, v69
	v_cvt_pk_bf16_f32 v44, v74, v75
	v_cvt_pk_bf16_f32 v45, v76, v77
	s_nop 1
	v_mfma_f32_16x16x32_bf16 v[38:41], v[42:45], v[54:57], v[38:41]
	v_or_b32_e32 v42, s96, v223
	v_sub_u32_e32 v43, v224, v42
	v_xad_u32 v44, v42, -1, v224
	v_sub_u32_e32 v45, v233, v42
	v_sub_u32_e32 v46, v234, v42
	v_sub_u32_e32 v47, v235, v42
	v_sub_u32_e32 v48, v236, v42
	v_sub_u32_e32 v49, v237, v42
	v_sub_u32_e32 v50, v238, v42
	v_med3_i32 v43, v43, 0, v243
	v_med3_i32 v44, v44, 0, v243
	v_med3_i32 v45, v45, 0, v243
	v_med3_i32 v46, v46, 0, v243
	v_med3_i32 v47, v47, 0, v243
	v_med3_i32 v48, v48, 0, v243
	v_med3_i32 v49, v49, 0, v243
	v_med3_i32 v50, v50, 0, v243
	v_lshl_add_u32 v43, v43, 2, s90
	v_lshl_add_u32 v44, v44, 2, s90
	v_lshl_add_u32 v45, v45, 2, s90
	v_lshl_add_u32 v46, v46, 2, s90
	v_lshl_add_u32 v47, v47, 2, s90
	v_lshl_add_u32 v48, v48, 2, s90
	v_lshl_add_u32 v49, v49, 2, s90
	v_lshl_add_u32 v50, v50, 2, s90
	v_cmp_ge_i32_e32 vcc, v224, v42
	ds_read_b32 v43, v43
	ds_read_b32 v44, v44
	ds_read_b32 v45, v45
	ds_read_b32 v46, v46
	ds_read_b32 v47, v47
	ds_read_b32 v48, v48
	ds_read_b32 v49, v49
	ds_read_b32 v50, v50
	s_and_b64 s[20:21], s[36:37], vcc
	s_waitcnt lgkmcnt(7)
; #define LAS __attribute__((address_space(3)))
; __device__ __forceinline__ unsigned pk2(float lo, float hi) { return pg8::cvt_pk_bf16(lo, hi); }
; __device__ __forceinline__ float ex2(float x) { return __builtin_amdgcn_exp2f(x); }
; #define MFMA16(a, b, c) __builtin_amdgcn_mfma_f32_16x16x32_bf16((a), (b), (c), 0, 0, 0)
; __device__ __forceinline__ bf16x8 cvt8(f32x4 a, f32x4 b) { v4u w = {pk2(a[0], a[1]), pk2(a[2], a[3]), pk2(b[0], b[1]), pk2(b[2], b[3])}; return __builtin_bit_cast(bf16x8, w); }
; __device__ __forceinline__ void decode_unit(int item, const float* ck, const float* cv, const int* pt, const bf16* QB, const float* ksamp, const float* vsamp, bf16* MIX_unused_, LAS unsigned char* lds, const LAS float* BL, float lam, float* PART, gu32* dcnt, bf16* MIX, gu32* rdy4) {
;     ...
;         asm volatile("s_waitcnt lgkmcnt(0)" ::: "memory");
; #pragma unroll
;         for (int sub = 0; sub < 2; ++sub)
; #pragma unroll
;             for (int r = 0; r < 4; ++r) { const int kl = 16 * sub + 4 * q + r; const int dist = PAST + tok - (key0c + kl);
;                 bool ok = n < 8; if (isnewc) ok = ok && kl < 4 && dist >= 0;
;                 const float e = ex2(s[sub][r] + bvs[sub][r]); p[sub][r] = ok ? e : 0.f; }
;         lsum += ((p[0][0] + p[0][1]) + (p[0][2] + p[0][3])) + ((p[1][0] + p[1][1]) + (p[1][2] + p[1][3]));
;         const bf16x8 pf = cvt8(p[0], p[1]);
; #pragma unroll
;         for (int hf = 0; hf < 2; ++hf)
; #pragma unroll
;             for (int c = 0; c < 4; ++c) { const v4u w = {pk2(vr[0][hf][c], vr[1][hf][c]), pk2(vr[2][hf][c], vr[3][hf][c]), pk2(vr[4][hf][c], vr[5][hf][c]), pk2(vr[6][hf][c], vr[7][hf][c])};
;                 O[hf * 4 + c] = MFMA16(pf, __builtin_bit_cast(bf16x8, w), O[hf * 4 + c]); }
;     }
;     ...
;     lsum += __shfl_xor(lsum, 16); lsum += __shfl_xor(lsum, 32);
;     LAS float* cb = (LAS float*)lds + h * (33 * 64);
;     if (kh == 1) {
; #pragma unroll
;         for (int c = 0; c < 8; ++c)
; #pragma unroll
;             for (int r = 0; r < 4; ++r) cb[(c * 4 + r) * 64 + lane] = O[c][r];
;         cb[32 * 64 + lane] = lsum;
;     }
	v_add_f32_e32 v34, v34, v43
	v_cndmask_b32_e64 v42, 0, 1, s[20:21]
	v_exp_f32_e32 v34, v34
	v_cndmask_b32_e64 v42, v219, v42, s[74:75]
	v_and_b32_e32 v42, 1, v42
	v_cmp_eq_u32_e32 vcc, 1, v42
	v_or_b32_e32 v42, s96, v226
	s_waitcnt lgkmcnt(6)
	v_add_f32_e32 v35, v35, v44
	v_cndmask_b32_e32 v34, 0, v34, vcc
	v_cmp_ge_i32_e32 vcc, v224, v42
	s_and_b64 s[20:21], s[36:37], vcc
	v_cndmask_b32_e64 v42, 0, 1, s[20:21]
	v_exp_f32_e32 v35, v35
	v_cndmask_b32_e64 v42, v219, v42, s[74:75]
	v_and_b32_e32 v42, 1, v42
	v_cmp_eq_u32_e32 vcc, 1, v42
	v_or_b32_e32 v42, s96, v228
	s_waitcnt lgkmcnt(5)
	v_add_f32_e32 v36, v36, v45
	v_cndmask_b32_e32 v35, 0, v35, vcc
	v_cmp_ge_i32_e32 vcc, v224, v42
	s_and_b64 s[20:21], s[36:37], vcc
	v_cndmask_b32_e64 v42, 0, 1, s[20:21]
	v_exp_f32_e32 v36, v36
	v_cndmask_b32_e64 v42, v219, v42, s[74:75]
	v_and_b32_e32 v42, 1, v42
	v_cmp_eq_u32_e32 vcc, 1, v42
	v_or_b32_e32 v42, s96, v231
	s_waitcnt lgkmcnt(4)
	v_add_f32_e32 v37, v37, v46
	v_cndmask_b32_e32 v36, 0, v36, vcc
	v_cmp_ge_i32_e32 vcc, v224, v42
	s_and_b64 s[20:21], s[36:37], vcc
	v_cndmask_b32_e64 v42, 0, 1, s[20:21]
	v_exp_f32_e32 v37, v37
	s_waitcnt lgkmcnt(3)
	v_add_f32_e32 v38, v38, v47
	s_waitcnt lgkmcnt(2)
	v_add_f32_e32 v39, v39, v48
	s_waitcnt lgkmcnt(1)
	v_add_f32_e32 v40, v40, v49
	s_waitcnt lgkmcnt(0)
	v_add_f32_e32 v41, v41, v50
	v_cndmask_b32_e64 v42, v219, v42, s[74:75]
	v_exp_f32_e32 v38, v38
	v_exp_f32_e32 v39, v39
	v_exp_f32_e32 v40, v40
	v_exp_f32_e32 v41, v41
	v_and_b32_e32 v42, 1, v42
	v_cmp_eq_u32_e32 vcc, 1, v42
	s_xor_b64 s[20:21], s[74:75], -1
	v_add_f32_e32 v42, v34, v35
	v_cndmask_b32_e32 v37, 0, v37, vcc
	s_and_b64 vcc, s[20:21], s[14:15]
	v_cndmask_b32_e32 v38, 0, v38, vcc
	v_cndmask_b32_e32 v39, 0, v39, vcc
	v_cndmask_b32_e32 v40, 0, v40, vcc
	v_cndmask_b32_e32 v41, 0, v41, vcc
	v_add_f32_e32 v43, v36, v37
	v_cvt_pk_bf16_f32 v34, v34, v35
	v_cvt_pk_bf16_f32 v35, v36, v37
	v_cvt_pk_bf16_f32 v36, v38, v39
	v_cvt_pk_bf16_f32 v37, v40, v41
	v_add_f32_e32 v42, v42, v43
	v_add_f32_e32 v43, v38, v39
	v_add_f32_e32 v44, v40, v41
	s_waitcnt vmcnt(13)
	v_cvt_pk_bf16_f32 v38, v132, v136
	s_waitcnt vmcnt(9)
	v_cvt_pk_bf16_f32 v39, v140, v144
	s_waitcnt vmcnt(5)
	v_cvt_pk_bf16_f32 v40, v148, v152
	s_waitcnt vmcnt(1)
	v_cvt_pk_bf16_f32 v41, v156, v160
	v_add_f32_e32 v43, v43, v44
	v_add_f32_e32 v42, v42, v43
	v_mfma_f32_16x16x32_bf16 v[30:33], v[34:37], v[38:41], v[30:33]
	v_cvt_pk_bf16_f32 v38, v133, v137
	v_cvt_pk_bf16_f32 v39, v141, v145
	v_cvt_pk_bf16_f32 v40, v149, v153
	v_cvt_pk_bf16_f32 v41, v157, v161
	v_add_f32_e32 v42, v215, v42
	s_waitcnt lgkmcnt(0)
	s_mul_i32 s20, s88, 0x2100
	v_mfma_f32_16x16x32_bf16 v[26:29], v[34:37], v[38:41], v[26:29]
	v_cvt_pk_bf16_f32 v38, v134, v138
	v_cvt_pk_bf16_f32 v39, v142, v146
	v_cvt_pk_bf16_f32 v40, v150, v154
	v_cvt_pk_bf16_f32 v41, v158, v162
	s_add_i32 s22, s20, 0
	s_cmp_lg_u32 s19, 1
	v_mfma_f32_16x16x32_bf16 v[22:25], v[34:37], v[38:41], v[22:25]
	v_cvt_pk_bf16_f32 v38, v135, v139
	v_cvt_pk_bf16_f32 v39, v143, v147
	v_cvt_pk_bf16_f32 v40, v151, v155
	v_cvt_pk_bf16_f32 v41, v159, v163
	s_nop 1
	v_mfma_f32_16x16x32_bf16 v[18:21], v[34:37], v[38:41], v[18:21]
	v_cvt_pk_bf16_f32 v38, v100, v104
	v_cvt_pk_bf16_f32 v39, v108, v112
	v_cvt_pk_bf16_f32 v40, v116, v120
	s_waitcnt vmcnt(0)
	v_cvt_pk_bf16_f32 v41, v124, v128
	s_nop 1
	v_mfma_f32_16x16x32_bf16 v[14:17], v[34:37], v[38:41], v[14:17]
	v_cvt_pk_bf16_f32 v38, v101, v105
	v_cvt_pk_bf16_f32 v39, v109, v113
	v_cvt_pk_bf16_f32 v40, v117, v121
	v_cvt_pk_bf16_f32 v41, v125, v129
	s_nop 1
	v_mfma_f32_16x16x32_bf16 v[10:13], v[34:37], v[38:41], v[10:13]
	v_cvt_pk_bf16_f32 v38, v102, v106
	v_cvt_pk_bf16_f32 v39, v110, v114
	v_cvt_pk_bf16_f32 v40, v118, v122
	v_cvt_pk_bf16_f32 v41, v126, v130
	s_nop 1
	v_mfma_f32_16x16x32_bf16 v[6:9], v[34:37], v[38:41], v[6:9]
	v_and_b32_e32 v39, 64, v1
	v_xor_b32_e32 v38, 16, v1
	v_add_u32_e32 v50, 64, v39
	v_cmp_lt_i32_e32 vcc, v38, v50
	v_cvt_pk_bf16_f32 v39, v111, v115
	v_cvt_pk_bf16_f32 v40, v119, v123
	v_cndmask_b32_e32 v38, v1, v38, vcc
	v_lshlrev_b32_e32 v38, 2, v38
	ds_bpermute_b32 v43, v38, v42
	v_cvt_pk_bf16_f32 v38, v103, v107
	v_cvt_pk_bf16_f32 v41, v127, v131
	s_waitcnt lgkmcnt(0)
	v_add_f32_e32 v42, v42, v43
	v_xor_b32_e32 v43, 32, v1
	v_cmp_lt_i32_e32 vcc, v43, v50
	v_mfma_f32_16x16x32_bf16 v[2:5], v[34:37], v[38:41], v[2:5]
	s_nop 0
	v_cndmask_b32_e32 v43, v1, v43, vcc
	v_lshlrev_b32_e32 v43, 2, v43
	ds_bpermute_b32 v43, v43, v42
	s_waitcnt lgkmcnt(0)
	v_add_f32_e32 v34, v42, v43
	s_cbranch_scc1 .LBB0_672
	v_lshl_add_u32 v35, v230, 2, s22
	ds_write2st64_b32 v35, v30, v31 offset1:1
	ds_write2st64_b32 v35, v32, v33 offset0:2 offset1:3
	ds_write2st64_b32 v35, v26, v27 offset0:4 offset1:5
	ds_write2st64_b32 v35, v28, v29 offset0:6 offset1:7
	ds_write2st64_b32 v35, v22, v23 offset0:8 offset1:9
	ds_write2st64_b32 v35, v24, v25 offset0:10 offset1:11
	ds_write2st64_b32 v35, v18, v19 offset0:12 offset1:13
	ds_write2st64_b32 v35, v20, v21 offset0:14 offset1:15
	ds_write2st64_b32 v35, v14, v15 offset0:16 offset1:17
	ds_write2st64_b32 v35, v16, v17 offset0:18 offset1:19
	ds_write2st64_b32 v35, v10, v11 offset0:20 offset1:21
	ds_write2st64_b32 v35, v12, v13 offset0:22 offset1:23
	ds_write2st64_b32 v35, v6, v7 offset0:24 offset1:25
	ds_write2st64_b32 v35, v8, v9 offset0:26 offset1:27
	ds_write2st64_b32 v35, v2, v3 offset0:28 offset1:29
	ds_write2st64_b32 v35, v4, v5 offset0:30 offset1:31
	ds_write_b32 v35, v34 offset:8192
